# gla_finish item epilogue: 8 gate/gain loads in flight, one wait, then math and 4 stores (was 8 serialized load-wait round trips)
# speedup vs baseline: 1.0011x; 1.0011x over previous
; DI int oidx(int i) { asm volatile("" : "+s"(i)); return i; }
; DI unsigned pack2(float a, float b) { unsigned r; asm volatile("v_cvt_pk_bf16_f32 %0, %1, %2" : "=v"(r) : "v"(a), "v"(b)); return r; }
; DN void gla_finish_item(const Params& p, int l, int b, int cs, int hh, char* smem) {
;     ...
;   {
;     float ss = 0.f;
; #pragma unroll
;     for (int i = 0; i < 16; ++i) ss += accO[i] * accO[i];
;     ss += __shfl_xor(ss, 32);
;     if (h == 0) ssq[w * 32 + r] = ss;
;     vsync_l();
;     const float tot = ssq[w * 32 + r] + ssq[(w ^ 2) * 32 + r];
;     const float rstd = rsqrtf(tot * (1.f / 64.f) + 1e-6f);
;     const size_t m = m0 + it * 32 + r;
;     const float* ng = p.in[oidx(26)] + l * 64;
; #pragma unroll
;     for (int g4 = 0; g4 < 4; ++g4) {
;       const int e0 = et * 32 + 8 * g4 + 4 * h;
;       const uint2 rw = *(const uint2*)(P + m * PW + 2464 + hh * 64 + e0);
;       const float rv[4] = {__uint_as_float(rw.x << 16), __uint_as_float(rw.x & 0xffff0000u), __uint_as_float(rw.y << 16), __uint_as_float(rw.y & 0xffff0000u)};
;       float ov[4];
; #pragma unroll
;       for (int q = 0; q < 4; ++q) ov[q] = accO[4 * g4 + q] * rstd * ng[e0 + q] * (rv[q] * __builtin_amdgcn_rcpf(1.f + __expf(-rv[q])));
;       uint2 pk; pk.x = pack2(ov[0], ov[1]); pk.y = pack2(ov[2], ov[3]);
;       *(uint2*)(O + m * DM + 512 + hh * 64 + e0) = pk;
;     }
;   }
.LBB0_1091:
	s_or_b64 exec, exec, s[2:3]
	v_or_b32_e32 v17, v16, v51
	v_bitop3_b32 v16, v16, 64, v51 bitop3:0x36
	v_lshl_add_u32 v17, v17, 2, s6
	v_lshl_add_u32 v16, v16, 2, s6
	ds_read_b32 v17, v17 offset:38144
	ds_read_b32 v16, v16 offset:38144
	v_readlane_b32 s2, v253, 41
	v_readlane_b32 s4, v253, 28
	v_readlane_b32 s5, v253, 29
	v_or_b32_e32 v152, s2, v58
	s_mov_b32 s2, 26
	s_waitcnt lgkmcnt(0)
	v_add_f32_e32 v16, v17, v16
	s_ashr_i32 s3, s2, 31
	v_fmamk_f32 v16, v16, 0x3c800000, v186
	s_lshl_b64 s[2:3], s[2:3], 3
	v_cmp_gt_f32_e32 vcc, s33, v16
	v_mul_f32_e32 v17, 0x4b800000, v16
	s_add_u32 s2, s0, s2
	v_cndmask_b32_e32 v16, v16, v17, vcc
	s_addc_u32 s3, s1, s3
	v_rsq_f32_e32 v16, v16
	s_load_dwordx2 s[2:3], s[2:3], 0x0
	s_lshl_b64 s[4:5], s[4:5], 2
	v_or_b32_e32 v18, v56, v57
	v_mul_f32_e32 v17, 0x45800000, v16
	v_cndmask_b32_e32 v24, v16, v17, vcc
	s_waitcnt lgkmcnt(0)
	s_add_u32 s2, s2, s4
	v_mov_b64_e32 v[16:17], s[84:85]
	s_addc_u32 s3, s3, s5
	v_mad_u64_u32 v[16:17], s[4:5], v152, s88, v[16:17]
	v_readlane_b32 s4, v253, 37
	v_readlane_b32 s5, v253, 38
	s_lshl_b32 s80, s4, 1
	v_ashrrev_i32_e32 v19, 31, v18
	v_lshl_add_u64 v[16:17], v[16:17], 0, s[80:81]
	s_load_dwordx4 s[4:7], s[0:1], 0x100
	v_lshlrev_b64 v[22:23], 1, v[18:19]
	v_lshl_add_u64 v[26:27], v[16:17], 0, v[22:23]
	s_waitcnt lgkmcnt(0)
	s_mov_b64 s[4:5], 0x1340
	v_lshl_add_u64 v[16:17], v[26:27], 0, s[4:5]
	v_add_co_u32_e32 v26, vcc, s96, v26
	v_lshl_add_u64 v[18:19], v[18:19], 2, s[2:3]
	s_nop 0
	v_addc_co_u32_e32 v27, vcc, 0, v27, vcc
	global_load_dwordx2 v[202:203], v[16:17], off
	global_load_dwordx2 v[204:205], v[16:17], off offset:16
	global_load_dwordx2 v[206:207], v[16:17], off offset:32
	global_load_dwordx2 v[208:209], v[16:17], off offset:48
	global_load_dwordx4 v[210:213], v[18:19], off
	global_load_dwordx4 v[214:217], v[18:19], off offset:32
	global_load_dwordx4 v[218:221], v[18:19], off offset:64
	global_load_dwordx4 v[222:225], v[18:19], off offset:96
	v_lshlrev_b64 v[20:21], 11, v[152:153]
	v_lshl_add_u64 v[20:21], s[6:7], 0, v[20:21]
	v_lshl_add_u64 v[20:21], v[20:21], 0, s[80:81]
	v_lshl_add_u64 v[20:21], v[20:21], 0, v[22:23]
	s_mov_b64 s[2:3], 0x2b7c500
	v_lshl_add_u64 v[226:227], v[20:21], 0, s[2:3]
	v_mul_f32_e32 v0, v0, v24
	v_mul_f32_e32 v1, v1, v24
	v_mul_f32_e32 v2, v2, v24
	v_mul_f32_e32 v3, v3, v24
	v_mul_f32_e32 v4, v4, v24
	v_mul_f32_e32 v5, v5, v24
	v_mul_f32_e32 v6, v6, v24
	v_mul_f32_e32 v7, v7, v24
	v_mul_f32_e32 v8, v8, v24
	v_mul_f32_e32 v9, v9, v24
	v_mul_f32_e32 v10, v10, v24
	v_mul_f32_e32 v11, v11, v24
	v_mul_f32_e32 v12, v12, v24
	v_mul_f32_e32 v13, v13, v24
	v_mul_f32_e32 v14, v14, v24
	v_mul_f32_e32 v15, v15, v24
	s_waitcnt vmcnt(0)
; DI unsigned pack2(float a, float b) { unsigned r; asm volatile("v_cvt_pk_bf16_f32 %0, %1, %2" : "=v"(r) : "v"(a), "v"(b)); return r; }
; DN void gla_finish_item(const Params& p, int l, int b, int cs, int hh, char* smem) {
;     ...
;     for (int g4 = 0; g4 < 4; ++g4) {
;       const int e0 = et * 32 + 8 * g4 + 4 * h;
;       const uint2 rw = *(const uint2*)(P + m * PW + 2464 + hh * 64 + e0);
;       const float rv[4] = {__uint_as_float(rw.x << 16), __uint_as_float(rw.x & 0xffff0000u), __uint_as_float(rw.y << 16), __uint_as_float(rw.y & 0xffff0000u)};
;       float ov[4];
; #pragma unroll
;       for (int q = 0; q < 4; ++q) ov[q] = accO[4 * g4 + q] * rstd * ng[e0 + q] * (rv[q] * __builtin_amdgcn_rcpf(1.f + __expf(-rv[q])));
;       uint2 pk; pk.x = pack2(ov[0], ov[1]); pk.y = pack2(ov[2], ov[3]);
;       *(uint2*)(O + m * DM + 512 + hh * 64 + e0) = pk;
;     }
	v_lshlrev_b32_e32 v228, 16, v202
	v_and_b32_e32 v229, 0xffff0000, v202
	v_lshlrev_b32_e32 v230, 16, v203
	v_and_b32_e32 v231, 0xffff0000, v203
	v_mul_f32_e32 v0, v210, v0
	v_mul_f32_e32 v1, v211, v1
	v_mul_f32_e32 v2, v212, v2
	v_mul_f32_e32 v3, v213, v3
	v_mul_f32_e32 v232, 0xbfb8aa3b, v228
	v_mul_f32_e32 v233, 0xbfb8aa3b, v229
	v_mul_f32_e32 v234, 0xbfb8aa3b, v230
	v_mul_f32_e32 v235, 0xbfb8aa3b, v231
	v_exp_f32_e32 v232, v232
	v_exp_f32_e32 v233, v233
	v_exp_f32_e32 v234, v234
	v_exp_f32_e32 v235, v235
	v_add_f32_e32 v232, 1.0, v232
	v_add_f32_e32 v233, 1.0, v233
	v_add_f32_e32 v234, 1.0, v234
	v_add_f32_e32 v235, 1.0, v235
	v_rcp_f32_e32 v232, v232
	v_rcp_f32_e32 v233, v233
	v_rcp_f32_e32 v234, v234
	v_rcp_f32_e32 v235, v235
	v_mul_f32_e32 v232, v232, v228
	v_mul_f32_e32 v233, v233, v229
	v_mul_f32_e32 v234, v234, v230
	v_mul_f32_e32 v235, v235, v231
	v_mul_f32_e32 v0, v0, v232
	v_mul_f32_e32 v1, v1, v233
	v_mul_f32_e32 v2, v2, v234
	v_mul_f32_e32 v3, v3, v235
	v_cvt_pk_bf16_f32 v236, v0, v1
	v_cvt_pk_bf16_f32 v237, v2, v3
	global_store_dwordx2 v[226:227], v[236:237], off
	s_nop 0
	v_lshlrev_b32_e32 v228, 16, v204
	v_and_b32_e32 v229, 0xffff0000, v204
	v_lshlrev_b32_e32 v230, 16, v205
	v_and_b32_e32 v231, 0xffff0000, v205
	v_mul_f32_e32 v4, v214, v4
	v_mul_f32_e32 v5, v215, v5
	v_mul_f32_e32 v6, v216, v6
	v_mul_f32_e32 v7, v217, v7
	v_mul_f32_e32 v232, 0xbfb8aa3b, v228
	v_mul_f32_e32 v233, 0xbfb8aa3b, v229
	v_mul_f32_e32 v234, 0xbfb8aa3b, v230
	v_mul_f32_e32 v235, 0xbfb8aa3b, v231
	v_exp_f32_e32 v232, v232
	v_exp_f32_e32 v233, v233
	v_exp_f32_e32 v234, v234
	v_exp_f32_e32 v235, v235
	v_add_f32_e32 v232, 1.0, v232
	v_add_f32_e32 v233, 1.0, v233
	v_add_f32_e32 v234, 1.0, v234
	v_add_f32_e32 v235, 1.0, v235
	v_rcp_f32_e32 v232, v232
	v_rcp_f32_e32 v233, v233
	v_rcp_f32_e32 v234, v234
	v_rcp_f32_e32 v235, v235
	v_mul_f32_e32 v232, v232, v228
	v_mul_f32_e32 v233, v233, v229
	v_mul_f32_e32 v234, v234, v230
	v_mul_f32_e32 v235, v235, v231
	v_mul_f32_e32 v4, v4, v232
	v_mul_f32_e32 v5, v5, v233
	v_mul_f32_e32 v6, v6, v234
	v_mul_f32_e32 v7, v7, v235
	v_cvt_pk_bf16_f32 v236, v4, v5
	v_cvt_pk_bf16_f32 v237, v6, v7
	global_store_dwordx2 v[226:227], v[236:237], off offset:16
	s_nop 0
	v_lshlrev_b32_e32 v228, 16, v206
	v_and_b32_e32 v229, 0xffff0000, v206
	v_lshlrev_b32_e32 v230, 16, v207
	v_and_b32_e32 v231, 0xffff0000, v207
	v_mul_f32_e32 v8, v218, v8
	v_mul_f32_e32 v9, v219, v9
	v_mul_f32_e32 v10, v220, v10
	v_mul_f32_e32 v11, v221, v11
	v_mul_f32_e32 v232, 0xbfb8aa3b, v228
	v_mul_f32_e32 v233, 0xbfb8aa3b, v229
	v_mul_f32_e32 v234, 0xbfb8aa3b, v230
	v_mul_f32_e32 v235, 0xbfb8aa3b, v231
	v_exp_f32_e32 v232, v232
	v_exp_f32_e32 v233, v233
	v_exp_f32_e32 v234, v234
	v_exp_f32_e32 v235, v235
	v_add_f32_e32 v232, 1.0, v232
	v_add_f32_e32 v233, 1.0, v233
	v_add_f32_e32 v234, 1.0, v234
	v_add_f32_e32 v235, 1.0, v235
	v_rcp_f32_e32 v232, v232
	v_rcp_f32_e32 v233, v233
	v_rcp_f32_e32 v234, v234
	v_rcp_f32_e32 v235, v235
	v_mul_f32_e32 v232, v232, v228
	v_mul_f32_e32 v233, v233, v229
	v_mul_f32_e32 v234, v234, v230
	v_mul_f32_e32 v235, v235, v231
	v_mul_f32_e32 v8, v8, v232
	v_mul_f32_e32 v9, v9, v233
	v_mul_f32_e32 v10, v10, v234
	v_mul_f32_e32 v11, v11, v235
	v_cvt_pk_bf16_f32 v236, v8, v9
	v_cvt_pk_bf16_f32 v237, v10, v11
	global_store_dwordx2 v[226:227], v[236:237], off offset:32
	s_nop 0
	v_lshlrev_b32_e32 v228, 16, v208
	v_and_b32_e32 v229, 0xffff0000, v208
	v_lshlrev_b32_e32 v230, 16, v209
	v_and_b32_e32 v231, 0xffff0000, v209
	v_mul_f32_e32 v12, v222, v12
	v_mul_f32_e32 v13, v223, v13
	v_mul_f32_e32 v14, v224, v14
	v_mul_f32_e32 v15, v225, v15
	v_mul_f32_e32 v232, 0xbfb8aa3b, v228
	v_mul_f32_e32 v233, 0xbfb8aa3b, v229
	v_mul_f32_e32 v234, 0xbfb8aa3b, v230
	v_mul_f32_e32 v235, 0xbfb8aa3b, v231
	v_exp_f32_e32 v232, v232
	v_exp_f32_e32 v233, v233
	v_exp_f32_e32 v234, v234
	v_exp_f32_e32 v235, v235
	v_add_f32_e32 v232, 1.0, v232
	v_add_f32_e32 v233, 1.0, v233
	v_add_f32_e32 v234, 1.0, v234
	v_add_f32_e32 v235, 1.0, v235
	v_rcp_f32_e32 v232, v232
	v_rcp_f32_e32 v233, v233
	v_rcp_f32_e32 v234, v234
	v_rcp_f32_e32 v235, v235
	v_mul_f32_e32 v232, v232, v228
	v_mul_f32_e32 v233, v233, v229
	v_mul_f32_e32 v234, v234, v230
	v_mul_f32_e32 v235, v235, v231
	v_mul_f32_e32 v12, v12, v232
	v_mul_f32_e32 v13, v13, v233
	v_mul_f32_e32 v14, v14, v234
	v_mul_f32_e32 v15, v15, v235
	v_cvt_pk_bf16_f32 v236, v12, v13
	v_cvt_pk_bf16_f32 v237, v14, v15
	global_store_dwordx2 v[226:227], v[236:237], off offset:48
